# static s_setprio 1 for waves 4-7 during the two mixer phases and the branch GEMM phase (reset at the phase loop top)
# speedup vs baseline: 1.0014x; 1.0014x over previous
; #define LAS __attribute__((address_space(3)))
; __device__ __forceinline__ unsigned xb_xcc_id() { return (unsigned)__builtin_amdgcn_s_getreg((3 << 11) | 20) & 0xFu; }
; #define GSYNC() xcd_barrier((unsigned*)lds_u64(&lp->bar), bst)
; __device__ __forceinline__ void xcd_barrier(unsigned* bar, volatile LAS unsigned* st) {
;     asm volatile("s_waitcnt vmcnt(0)" ::: "memory");
;     __syncthreads();
;     if (threadIdx.x == 0) {
;         const unsigned x = xb_xcc_id();
;         __builtin_amdgcn_s_waitcnt(0);
;         unsigned nloc = st[0], nx = st[1];
;         if (nloc == 0u) { xcd_barrier_complete(bar, x, nloc, nx); st[0] = nloc; st[1] = nx; }
; __global__ void __launch_bounds__(512, 2) mega(Params p) {
;     ...
;     for (int ph = lo; ph < hi; ++ph) {
;         if (ph > lo) { if (hi > 4096) grid.sync(); else GSYNC(); }
.LBB0_10:
	s_setprio 0
	s_cmp_le_i32 s94, s33
	s_cbranch_scc1 .LBB0_70
	v_readlane_b32 s0, v255, 4
	v_readlane_b32 s1, v255, 5
	s_mov_b64 s[4:5], -1
	s_and_b64 vcc, exec, s[0:1]
	s_cbranch_vccz .LBB0_57
	v_readlane_b32 s0, v255, 6
	s_nop 1
	v_mov_b32_e32 v0, s0
	ds_read_b64 v[0:1], v0
	s_waitcnt vmcnt(0)
	s_waitcnt lgkmcnt(0)
	s_barrier
	v_readfirstlane_b32 s72, v0
	v_readfirstlane_b32 s73, v1
	s_mov_b64 s[70:71], exec
	v_readlane_b32 s0, v255, 2
	v_readlane_b32 s1, v255, 3
	s_and_b64 s[0:1], s[70:71], s[0:1]
	s_mov_b64 exec, s[0:1]
	s_cbranch_execz .LBB0_56
	v_readlane_b32 s1, v255, 7
	s_getreg_b32 s0, hwreg(HW_REG_XCC_ID, 0, 4)
	s_waitcnt vmcnt(0) expcnt(0) lgkmcnt(0)
	v_mov_b32_e32 v0, s1
	ds_read_b32 v4, v0
	v_readlane_b32 s1, v255, 8
	s_and_b32 s0, s0, 15
	s_waitcnt lgkmcnt(0)
	v_cmp_ne_u32_e32 vcc, 0, v4
	v_mov_b32_e32 v0, s1
	ds_read_b32 v0, v0
	s_cbranch_vccnz .LBB0_27
	s_add_u32 s2, s72, 0x1000
	s_addc_u32 s3, s73, 0
	s_add_u32 s6, s72, 0x1100
	s_addc_u32 s7, s73, 0
	s_add_u32 s8, s72, 0x1200
	s_addc_u32 s9, s73, 0
	s_add_u32 s10, s72, 0x1300
	s_addc_u32 s11, s73, 0
	s_mov_b32 s1, 1
	s_mov_b64 s[4:5], 0
	s_waitcnt lgkmcnt(0)
	v_mov_b64_e32 v[0:1], s[72:73]
	v_mov_b64_e32 v[4:5], s[2:3]
	v_mov_b64_e32 v[6:7], s[6:7]
	v_mov_b64_e32 v[8:9], s[8:9]
	v_mov_b64_e32 v[10:11], s[10:11]
	s_branch .LBB0_17

; __device__ __forceinline__ int opaque_tid() { int t = threadIdx.x; asm volatile("" : "+v"(t)); return t; }
; __device__ __forceinline__ Params fetchP(const LAS Params* lp0) { unsigned la = (unsigned)(unsigned long long)lp0; asm volatile("" : "+v"(la)); const LAS Params* lp = (const LAS Params*)la; Params q; PFIELDS(PFETCH) q.ph_lo = 0; q.ph_hi = 0; return q; }
; __device__ __forceinline__ void bgemm_phase(LAS unsigned char* lds, const bf16_t* outs, const bf16_t* wbr, const bf16_t* zg, bf16_t* merged) {
;     ...
;     const int tid = opaque_tid(), wid = __builtin_amdgcn_readfirstlane(tid >> 6), lane = tid & 63, fr = lane & 15, fq = lane >> 4;
;     const int wm = wid >> 1, wn = wid & 1;
;     unsigned voff[2], voffB[2];
; #pragma unroll
;     for (int i = 0; i < 2; ++i) { int R, C; stage_rc(tid * 16 + i * 8192, R, C); voff[i] = (unsigned)(R * 256 + C) * 2u; voffB[i] = (unsigned)(((R & ~31) + perm32(R & 31)) * 256 + C) * 2u; }
;     const unsigned ldsw = (unsigned)wid * 1024u;
;     const int aoff = (wm >> 1) * HTB + lds_byte((wm & 1) * 64 + fr, fq * 8);
;     const int boff = 2 * HTB + lds_byte(wn * 64 + fr, fq * 8);
;     constexpr int STG = 3 * HTB;
; __device__ __forceinline__ void run_phase(const LAS Params* lp, int ph, LAS unsigned char* lds) {
;     ...
;     case 3: { const Params p = fetchP(lp); bgemm_phase(lds, p.outs, p.wt_br + (size_t)l * 4096 * 256, p.z + ZG_OFF, p.hbuf); } break;
.LBB0_292:
	s_and_b64 vcc, exec, s[4:5]
	s_cbranch_vccz .LBB0_299
	v_mov_b32_e32 v0, s84
	s_waitcnt vmcnt(0)
	ds_read2_b64 v[4:7], v0 offset0:25 offset1:31
	ds_read2_b64 v[8:11], v0 offset0:29 offset1:30
	v_mov_b32_e32 v1, v202
	s_mov_b32 s0, s91
	v_mov_b32_e32 v203, 1
	v_mov_b32_e32 v210, 0xb00000
	v_mov_b32_e32 v212, 0x80
	v_mov_b32_e32 v254, 0xc0
	s_waitcnt lgkmcnt(0)
	v_readfirstlane_b32 s2, v4
	v_readfirstlane_b32 s8, v5
	v_readfirstlane_b32 s9, v8
	v_readfirstlane_b32 s12, v9
	v_readfirstlane_b32 s4, v10
	v_readfirstlane_b32 s5, v11
	v_readfirstlane_b32 s6, v6
	v_readfirstlane_b32 s7, v7
	s_cmpk_gt_i32 s0, 0x1ff
	v_readfirstlane_b32 s13, v1
	s_cbranch_scc1 .LBB0_298
	v_readlane_b32 s14, v255, 22
	v_readlane_b32 s15, v255, 23
	s_mov_b32 s16, s14
	s_ashr_i32 s17, s14, 31
	v_writelane_b32 v255, s14, 22
	v_and_b32_e32 v4, 15, v1
	v_bfe_u32 v5, v1, 4, 2
	v_writelane_b32 v255, s15, 23
	s_lshl_b64 s[14:15], s[16:17], 21
	s_add_u32 s2, s2, s14
	s_addc_u32 s23, s8, s15
	s_add_u32 s8, s9, 0x5800000
	s_addc_u32 s9, s12, 0
	s_ashr_i32 s14, s13, 7
	s_ashr_i32 s12, s13, 6
	s_lshl_b32 s13, s13, 6
	s_lshl_b32 s16, s14, 13
	v_lshlrev_b32_e32 v3, 2, v1
	s_and_b32 s13, s13, 0xffffc000
	v_lshlrev_b32_e32 v0, 6, v4
	v_lshlrev_b32_e32 v6, 4, v5
	s_and_b32 s16, s16, 0x2000
	v_and_b32_e32 v8, 32, v3
	s_and_b32 s15, s12, 1
	v_or_b32_e32 v7, v6, v0
	v_bitop3_b32 v0, v6, v8, v0 bitop3:0x36
	s_or_b32 s13, s16, s13
	v_or_b32_e32 v3, s13, v0
	s_lshl_b32 s13, s15, 13
	v_bitop3_b32 v145, v7, s13, v8 bitop3:0xde
	v_lshlrev_b32_e32 v7, 4, v1
	v_add_u32_e32 v0, 0x2000, v7
	v_ashrrev_i32_e32 v8, 31, v0
	v_lshrrev_b32_e32 v8, 22, v8
	v_add_u32_e32 v8, v0, v8
	v_ashrrev_i32_e32 v8, 10, v8
	v_mul_i32_i24_e32 v9, 0x400, v8
	v_sub_u32_e32 v0, v0, v9
	v_lshrrev_b32_e32 v9, 4, v0
	v_bitop3_b32 v0, v9, v0, 32 bitop3:0x6c
	v_ashrrev_i32_e32 v9, 31, v0
	v_lshrrev_b32_e32 v9, 26, v9
	v_add_u32_e32 v9, v0, v9
	v_ashrrev_i32_e32 v10, 6, v9
	v_and_b32_e32 v9, 0xc0, v9
	v_sub_u32_e32 v0, v0, v9
	v_mov_b32_e32 v23, 1
	v_lshlrev_b32_e32 v11, 3, v8
	v_lshlrev_b32_e32 v17, 5, v8
	v_ashrrev_i16_sdwa v0, v23, sext(v0) dst_sel:DWORD dst_unused:UNUSED_PAD src0_sel:DWORD src1_sel:BYTE_0
	v_and_b32_e32 v11, -16, v11
	v_and_b32_e32 v17, 32, v17
	v_bfe_i32 v9, v0, 0, 16
	v_add_u32_e32 v11, v10, v11
	v_add_lshl_u32 v17, v17, v9, 1
	v_and_b32_e32 v12, 0x7fffe0, v11
	v_lshrrev_b32_e32 v15, 2, v11
	v_lshlrev_b32_e32 v16, 1, v11
	v_lshl_add_u32 v100, v11, 9, v17
	v_bfe_i32 v11, v1, 27, 1
	v_and_b32_e32 v13, 3, v10
	v_lshrrev_b32_e32 v11, 22, v11
	v_or_b32_e32 v14, v12, v13
	v_and_b32_e32 v15, 4, v15
	v_and_b32_e32 v16, 24, v16
	v_add_u32_e32 v11, v7, v11
	v_or3_b32 v14, v14, v15, v16
	v_and_b32_e32 v11, 0xfffffc00, v11
	v_lshl_add_u32 v0, v14, 9, v17
	v_sub_u32_e32 v7, v7, v11
	v_ashrrev_i32_e32 v14, 31, v1
	v_lshrrev_b32_e32 v11, 4, v7
	v_lshrrev_b32_e32 v14, 26, v14
	v_bitop3_b32 v11, v11, v7, 32 bitop3:0x6c
	v_ashrrev_i32_e32 v7, 31, v7
	v_add_u32_e32 v14, v1, v14
	v_lshrrev_b32_e32 v7, 26, v7
	v_ashrrev_i32_e32 v1, 6, v14
	v_add_u32_e32 v7, v11, v7
	v_lshlrev_b32_e32 v17, 3, v1
	v_ashrrev_i32_e32 v7, 6, v7
	v_and_b32_e32 v17, -16, v17
	v_add_u32_e32 v17, v7, v17
	v_and_b32_e32 v19, 3, v7
	v_mul_i32_i24_e32 v7, 64, v7
	s_lshl_b32 s12, s12, 10
	v_sub_u32_e32 v7, v11, v7
	v_and_b32_e32 v18, 0x7fffe0, v17
	v_lshrrev_b32_e32 v21, 2, v17
	v_lshlrev_b32_e32 v22, 1, v17
	v_lshlrev_b32_e32 v1, 5, v1
	v_ashrrev_i16_sdwa v7, v23, sext(v7) dst_sel:DWORD dst_unused:UNUSED_PAD src0_sel:DWORD src1_sel:BYTE_0
	s_add_i32 s30, s12, 0
	s_lshl_b32 s12, s14, 10
	s_lshl_b32 s13, s15, 7
	v_or_b32_e32 v20, v18, v19
	v_and_b32_e32 v21, 4, v21
	v_and_b32_e32 v22, 24, v22
	v_and_b32_e32 v1, 32, v1
	v_bfe_i32 v7, v7, 0, 16
	s_or_b32 s12, s13, s12
	v_lshl_or_b32 v215, s14, 6, v4
	v_or3_b32 v20, v20, v21, v22
	v_add_lshl_u32 v1, v1, v7, 1
	v_or3_b32 v4, s12, v6, v4
	v_lshl_add_u32 v102, v20, 9, v1
	v_lshl_add_u32 v104, v17, 9, v1
	v_lshlrev_b32_e32 v1, 3, v5
	v_ashrrev_i32_e32 v5, 31, v4
	v_lshlrev_b64 v[106:107], 3, v[4:5]
	v_or_b32_e32 v4, v12, v16
	v_lshlrev_b32_e32 v5, 6, v8
	v_or3_b32 v4, v4, v15, v13
	v_and_b32_e32 v5, 64, v5
	v_lshl_or_b32 v4, v4, 9, v5
	v_lshlrev_b32_e32 v6, 1, v9
	v_add_u32_e32 v108, v4, v6
	v_or_b32_e32 v4, v18, v22
	v_or3_b32 v4, v4, v21, v19
	v_and_b32_e32 v9, 64, v14
	v_lshl_or_b32 v4, v4, 9, v9
	v_lshl_add_u32 v110, v7, 1, v4
	v_lshlrev_b32_e32 v4, 12, v8
	v_and_b32_e32 v4, 0xffffe000, v4
	v_lshl_add_u32 v4, v10, 9, v4
	v_or_b32_e32 v4, v4, v5
	v_mov_b32_e32 v105, v2
	v_add_u32_e32 v4, v4, v6
	v_mov_b32_e32 v5, v2
	v_or_b32_e32 v214, 0x8000, v145
	v_mov_b32_e32 v203, 1
	v_lshl_or_b32 v216, s15, 6, v1
	v_mov_b32_e32 v101, v2
	v_mov_b32_e32 v103, v2
	v_mov_b32_e32 v1, v2
	s_add_i32 s31, s30, 0x18000
	s_add_i32 s34, s30, 0x1a000
	v_mov_b32_e32 v109, v2
	v_mov_b32_e32 v111, v2
	v_lshl_add_u64 v[112:113], s[6:7], 0, v[4:5]
	v_lshl_add_u64 v[114:115], s[6:7], 0, v[104:105]
	v_readfirstlane_b32 s98, v202
	s_cmp_lt_u32 s98, 0x100
	s_cbranch_scc1 .Lsprio_bg
	s_setprio 1
; __device__ __forceinline__ int opaque_bid() { int t = blockIdx.x; asm volatile("" : "+s"(t)); return t; }
; __device__ __forceinline__ int opaque_gd() { int t = gridDim.x; asm volatile("" : "+s"(t)); return t; }
; #define BG_STAGE(kk_, slot_) do { const int _n = (kk_) >> 2, _kt = (kk_) & 3; const int _so = (slot_) * STG; \
;         const bf16_t* _a = outs + ((size_t)_n * M + (size_t)pm * 256) * 256 + _kt * 64; const bf16_t* _b = wbr + ((size_t)_n * 1024 + (size_t)pn * 128) * 256 + _kt * 64; \
;         BG_LD(_so, _a); BG_LD(_so + HTB, _a + 128 * 256); BG_LDX(_so + 2 * HTB, _b, voffB); } while (0)
; __device__ __forceinline__ void bgemm_phase(LAS unsigned char* lds, const bf16_t* outs, const bf16_t* wbr, const bf16_t* zg, bf16_t* merged) {
;     ...
;     for (int u = opaque_bid(); u < 512; u += opaque_gd()) {
;         const int up = (u & ~255) + (u & 7) * 32 + ((u & 255) >> 3);
;         const int pm = up >> 3, pn = up & 7;
;         f32x4 tot[4][4], acc[4][4];
; #pragma unroll
;         for (int mi = 0; mi < 4; ++mi)
; #pragma unroll
;             for (int ni = 0; ni < 4; ++ni) { tot[mi][ni] = ZERO4; acc[mi][ni] = ZERO4; }
;         BG_STAGE(0, 0); BG_STAGE(1, 1);
.Lsprio_bg:
.LBB0_295:
	s_lshl_b32 s13, s0, 5
	s_and_b32 s12, s0, 0xffffff00
	s_and_b32 s13, s13, 0xe0
	s_or_b32 s12, s13, s12
	s_lshr_b32 s13, s0, 3
	s_and_b32 s13, s13, 24
	s_or_b32 s35, s12, s13
	s_ashr_i32 s12, s35, 3
	s_ashr_i32 s13, s12, 31
	s_bfe_u32 s36, s0, 0x30003
	s_lshl_b64 s[16:17], s[12:13], 17
	s_add_u32 s14, s6, s16
	s_addc_u32 s15, s7, s17
	s_lshl_b32 s20, s36, 16
	s_add_i32 s42, s30, 0x2000
	s_mov_b32 m0, s30
	v_lshl_add_u64 v[4:5], s[14:15], 0, v[104:105]
	s_add_u32 s18, s14, 0x10000
	global_load_lds_dwordx4 v[4:5], off
	v_lshl_add_u64 v[6:7], s[14:15], 0, v[100:101]
	s_mov_b32 m0, s42
	s_addc_u32 s19, s15, 0
	s_add_i32 s41, s30, 0x4000
	global_load_lds_dwordx4 v[6:7], off
	v_lshl_add_u64 v[8:9], s[18:19], 0, v[104:105]
	s_mov_b32 m0, s41
	s_add_i32 s40, s30, 0x6000
	global_load_lds_dwordx4 v[8:9], off
	v_lshl_add_u64 v[8:9], s[18:19], 0, v[100:101]
	s_add_u32 s18, s2, s20
	s_mov_b32 m0, s40
	s_addc_u32 s19, s23, 0
	s_add_i32 s39, s30, 0x8000
	global_load_lds_dwordx4 v[8:9], off
	v_lshl_add_u64 v[8:9], s[18:19], 0, v[102:103]
	s_mov_b32 m0, s39
	s_add_i32 s38, s30, 0xa000
	global_load_lds_dwordx4 v[8:9], off
	v_lshl_add_u64 v[10:11], s[18:19], 0, v[0:1]
	s_mov_b32 m0, s38
	v_lshl_add_u64 v[4:5], v[4:5], 0, s[46:47]
	global_load_lds_dwordx4 v[10:11], off
	s_add_i32 m0, s30, 0xc000
	v_mov_b32_e32 v116, 0
	global_load_lds_dwordx4 v[4:5], off
	s_add_i32 m0, s30, 0xe000
	s_add_u32 s20, s14, 0x10080
	v_lshl_add_u64 v[4:5], v[6:7], 0, s[46:47]
	s_addc_u32 s21, s15, 0
	global_load_lds_dwordx4 v[4:5], off
	v_lshl_add_u64 v[4:5], s[20:21], 0, v[104:105]
	s_add_i32 m0, s30, 0x10000
	s_lshl_b32 s37, s36, 15
	global_load_lds_dwordx4 v[4:5], off
	v_lshl_add_u64 v[4:5], s[20:21], 0, v[100:101]
	s_add_i32 m0, s30, 0x12000
	s_lshl_b64 s[12:13], s[12:13], 18
	global_load_lds_dwordx4 v[4:5], off
	v_lshl_add_u64 v[4:5], v[8:9], 0, s[46:47]
	s_add_i32 m0, s30, 0x14000
	s_or_b32 s20, s12, s37
	global_load_lds_dwordx4 v[4:5], off
	v_lshl_add_u64 v[4:5], v[10:11], 0, s[46:47]
	s_add_i32 m0, s30, 0x16000
	s_mov_b32 s21, s13
	global_load_lds_dwordx4 v[4:5], off
	v_lshl_add_u64 v[194:195], s[20:21], 0, v[106:107]
	v_lshl_add_u64 v[196:197], v[112:113], 0, s[16:17]
	v_lshl_add_u64 v[198:199], v[114:115], 0, s[16:17]
	s_mov_b32 s16, 0
	s_mov_b64 s[20:21], 0
	s_mov_b64 s[26:27], s[18:19]
	v_mov_b32_e32 v117, v116
	v_mov_b32_e32 v118, v116
	v_mov_b32_e32 v119, v116
	v_mov_b32_e32 v120, v116
	v_mov_b32_e32 v121, v116
	v_mov_b32_e32 v122, v116
	v_mov_b32_e32 v123, v116
	v_mov_b32_e32 v124, v116
	v_mov_b32_e32 v125, v116
	v_mov_b32_e32 v126, v116
	v_mov_b32_e32 v127, v116
	v_mov_b32_e32 v128, v116
	v_mov_b32_e32 v129, v116
	v_mov_b32_e32 v130, v116
	v_mov_b32_e32 v131, v116
	v_mov_b32_e32 v146, v116
	v_mov_b32_e32 v147, v116
	v_mov_b32_e32 v148, v116
	v_mov_b32_e32 v149, v116
	v_mov_b32_e32 v150, v116
	v_mov_b32_e32 v151, v116
	v_mov_b32_e32 v152, v116
	v_mov_b32_e32 v153, v116
	v_mov_b32_e32 v154, v116
	v_mov_b32_e32 v155, v116
	v_mov_b32_e32 v156, v116
	v_mov_b32_e32 v157, v116
	v_mov_b32_e32 v158, v116
	v_mov_b32_e32 v159, v116
	v_mov_b32_e32 v160, v116
	v_mov_b32_e32 v161, v116
	v_mov_b32_e32 v162, v116
	v_mov_b32_e32 v163, v116
	v_mov_b32_e32 v164, v116
	v_mov_b32_e32 v165, v116
	v_mov_b32_e32 v166, v116
	v_mov_b32_e32 v167, v116
	v_mov_b32_e32 v168, v116
	v_mov_b32_e32 v169, v116
	v_mov_b32_e32 v170, v116
	v_mov_b32_e32 v171, v116
	v_mov_b32_e32 v172, v116
	v_mov_b32_e32 v173, v116
	v_mov_b32_e32 v174, v116
	v_mov_b32_e32 v175, v116
	v_mov_b32_e32 v176, v116
	v_mov_b32_e32 v177, v116
	v_mov_b32_e32 v178, v116
	v_mov_b32_e32 v179, v116
	v_mov_b32_e32 v180, v116
	v_mov_b32_e32 v181, v116
	v_mov_b32_e32 v182, v116
	v_mov_b32_e32 v183, v116
	v_mov_b32_e32 v184, v116
	v_mov_b32_e32 v185, v116
	v_mov_b32_e32 v186, v116
	v_mov_b32_e32 v187, v116
	v_mov_b32_e32 v188, v116
	v_mov_b32_e32 v189, v116
	v_mov_b32_e32 v190, v116
	v_mov_b32_e32 v191, v116
	v_mov_b32_e32 v192, v116
	v_mov_b32_e32 v193, v116

; __device__ __forceinline__ int opaque_bid() { int t = blockIdx.x; asm volatile("" : "+s"(t)); return t; }
; __device__ __forceinline__ int opaque_gd() { int t = gridDim.x; asm volatile("" : "+s"(t)); return t; }
; __device__ __forceinline__ Params fetchP(const LAS Params* lp0) { unsigned la = (unsigned)(unsigned long long)lp0; asm volatile("" : "+v"(la)); const LAS Params* lp = (const LAS Params*)la; Params q; PFIELDS(PFETCH) q.ph_lo = 0; q.ph_hi = 0; return q; }
; __device__ __forceinline__ void run_phase(const LAS Params* lp, int ph, LAS unsigned char* lds) {
;     ...
;     const int l = (ph - 1) / 7, s = (ph - 1) - l * 7;
;     const int G = opaque_gd(), c = opaque_bid();
;     switch (s) {
;     case 0: { const Params p = fetchP(lp); pg8::Gemm g{p.hbuf, p.wt_in + (size_t)l * 6912 * 1024, M, 6912, 1024, 30, 0}; pg8::EpiZG E{p.z, p.z + ZG_OFF}; pg8::gemm_phase(lds, g, G, c, E);
;               if (l < 3 && G == 256 && c >= 192) conv_range(p, lds, (l + 1) * 4352, (l + 1) * 4352 + 1152, c - 192, 64); } break;
;     case 1: for (int it = opaque_bid(); it < 1280; it += opaque_gd()) { const Params p = fetchP(lp); const int jx = (it & ~255) + (it & 7) * 32 + ((it & 255) >> 3);
;             if (it < 256) hgrn_item(p, l, jx, 0, lds); else if (it < 768) attn_item(p, l, jx - 256, lds); else lru_item(p, l, jx - 768, lds); } break;
;     case 2: for (int it = opaque_bid(); it < 1280; it += opaque_gd()) { const Params p = fetchP(lp); const int jx = (it & ~255) + (it & 7) * 32 + ((it & 255) >> 3);
;             if (it < 256) hgrn_item(p, l, jx, 1, lds); else if (it < 768) gmlp_item(p, l, jx - 256, lds); else lru_fix_item(p, l, jx - 768); } break;
.LBB0_300:
	s_and_b64 vcc, exec, s[4:5]
	s_cbranch_vccz .LBB0_430
	s_cmp_gt_i32 s88, 0
	s_mov_b64 s[4:5], -1
	s_cbranch_scc0 .LBB0_428
	s_cmp_gt_i32 s88, 1
	s_cbranch_scc0 .LBB0_348
	s_mov_b32 s72, s91
	s_cmpk_gt_i32 s72, 0x4ff
	s_cbranch_scc1 .LBB0_347
	v_readlane_b32 s4, v255, 22
	v_readlane_b32 s5, v255, 23
	s_mov_b32 s0, s4
	s_ashr_i32 s5, s4, 31
	v_writelane_b32 v255, s0, 22
	s_lshl_b32 s28, s4, 8
	s_lshl_b64 s[26:27], s[4:5], 9
	v_writelane_b32 v255, s1, 23
	s_ashr_i32 s29, s28, 31
	v_readfirstlane_b32 s98, v202
	s_cmp_lt_u32 s98, 0x100
	s_cbranch_scc1 .Lsprio_m2
	s_setprio 1
.Lsprio_m2:
	s_branch .LBB0_307

; __device__ __forceinline__ int opaque_bid() { int t = blockIdx.x; asm volatile("" : "+s"(t)); return t; }
; __device__ __forceinline__ int opaque_gd() { int t = gridDim.x; asm volatile("" : "+s"(t)); return t; }
; __device__ __forceinline__ Params fetchP(const LAS Params* lp0) { unsigned la = (unsigned)(unsigned long long)lp0; asm volatile("" : "+v"(la)); const LAS Params* lp = (const LAS Params*)la; Params q; PFIELDS(PFETCH) q.ph_lo = 0; q.ph_hi = 0; return q; }
; __device__ __forceinline__ void run_phase(const LAS Params* lp, int ph, LAS unsigned char* lds) {
;     ...
;     const int l = (ph - 1) / 7, s = (ph - 1) - l * 7;
;     const int G = opaque_gd(), c = opaque_bid();
;     switch (s) {
;     case 0: { const Params p = fetchP(lp); pg8::Gemm g{p.hbuf, p.wt_in + (size_t)l * 6912 * 1024, M, 6912, 1024, 30, 0}; pg8::EpiZG E{p.z, p.z + ZG_OFF}; pg8::gemm_phase(lds, g, G, c, E);
;               if (l < 3 && G == 256 && c >= 192) conv_range(p, lds, (l + 1) * 4352, (l + 1) * 4352 + 1152, c - 192, 64); } break;
;     case 1: for (int it = opaque_bid(); it < 1280; it += opaque_gd()) { const Params p = fetchP(lp); const int jx = (it & ~255) + (it & 7) * 32 + ((it & 255) >> 3);
;             if (it < 256) hgrn_item(p, l, jx, 0, lds); else if (it < 768) attn_item(p, l, jx - 256, lds); else lru_item(p, l, jx - 768, lds); } break;
.LBB0_348:
	s_andn2_b64 vcc, exec, s[4:5]
	s_cbranch_vccnz .LBB0_427
	s_mov_b32 s2, s91
	s_cmpk_gt_i32 s2, 0x4ff
	s_cbranch_scc1 .LBB0_427
	v_readlane_b32 s4, v255, 22
	v_readlane_b32 s5, v255, 23
	s_mov_b32 s0, s4
	s_ashr_i32 s5, s4, 31
	v_writelane_b32 v255, s0, 22
	s_lshl_b64 s[12:13], s[4:5], 8
	s_lshl_b32 s40, s4, 8
	s_lshl_b32 s87, s4, 10
	v_writelane_b32 v255, s1, 23
	s_lshl_b64 s[4:5], s[4:5], 2
	v_writelane_b32 v255, s4, 14
	s_mov_b32 s68, s94
	s_mov_b32 s43, s97
	v_writelane_b32 v255, s5, 15
	v_readfirstlane_b32 s98, v202
	s_cmp_lt_u32 s98, 0x100
	s_cbranch_scc1 .Lsprio_m1
	s_setprio 1
